# scoring loop: s_setprio 1/0 bracket around each tile's four-MFMA chain (priority lever, per-segment form)
# speedup vs baseline: 1.0066x; 1.0066x over previous
.LBB0_416:
	s_add_i32 s47, s46, -6
	s_cmp_lt_u32 s47, s81
	s_cbranch_scc0 .LBB0_439
	s_waitcnt vmcnt(8)
	s_setprio 1
	v_mfma_f32_32x32x16_bf16 v[0:15], v[28:31], v[36:39], 0
	v_cmp_le_i32_e32 vcc, v118, v114
	v_mfma_f32_32x32x16_bf16 v[0:15], v[20:23], v[32:35], v[0:15]
	v_mfma_f32_32x32x16_bf16 v[0:15], v[16:19], v[44:47], v[0:15]
	v_mfma_f32_32x32x16_bf16 v[0:15], v[24:27], v[40:43], v[0:15]
	s_setprio 0
	s_add_i32 s47, s46, -6
	s_add_i32 s44, s46, -3
	s_cmp_lt_u32 s44, s81
	s_cselect_b64 s[42:43], -1, 0
	s_and_b64 s[36:37], s[42:43], exec
	s_cselect_b32 s36, s44, s39
	s_lshl_b32 s36, s36, 5
	s_add_i32 s36, s36, s76
	s_ashr_i32 s37, s36, 31
	s_lshl_b64 s[44:45], s[36:37], 10
	v_lshl_add_u64 v[244:245], v[96:97], 0, s[44:45]
	s_or_b32 s44, s36, 1
	s_ashr_i32 s45, s44, 31
	s_lshl_b64 s[44:45], s[44:45], 10
	v_lshl_add_u64 v[246:247], v[96:97], 0, s[44:45]
	s_or_b32 s44, s36, 2
	s_ashr_i32 s45, s44, 31
	s_or_b32 s36, s36, 3
	s_lshl_b64 s[44:45], s[44:45], 10
	s_ashr_i32 s37, s36, 31
	global_load_dwordx4 v[84:87], v[244:245], off
	global_load_dwordx4 v[80:83], v[246:247], off
	v_lshl_add_u64 v[244:245], v[96:97], 0, s[44:45]
	s_lshl_b64 s[36:37], s[36:37], 10
	v_lshl_add_u64 v[246:247], v[96:97], 0, s[36:37]
	global_load_dwordx4 v[88:91], v[244:245], off
	global_load_dwordx4 v[92:95], v[246:247], off
	s_nop 3
	v_max_i32_e32 v33, 0, v4
	v_max_i32_e32 v32, 0, v0
	v_max_i32_e32 v0, 0, v5
	v_max_i32_e32 v5, 0, v6
	v_max_i32_e32 v34, 0, v8
	v_max_i32_e32 v36, 0, v1
	v_max_i32_e32 v4, 0, v2
	v_max_i32_e32 v8, 0, v10
	v_max_i32_e32 v1, 0, v7
	v_max_i32_e32 v7, 0, v11
	v_max_i32_e32 v11, 0, v15
	v_mul_f32_e32 v2, v99, v33
	v_mul_f32_e32 v10, v101, v5
	v_max_i32_e32 v35, 0, v12
	v_max_i32_e32 v37, 0, v9
	v_max_i32_e32 v9, 0, v14
	v_max_i32_e32 v14, 0, v3
	v_pk_fma_f32 v[2:3], v[98:99], v[32:33], v[2:3] op_sel_hi:[1,1,0]
	v_pk_fma_f32 v[4:5], v[100:101], v[4:5], v[10:11] op_sel_hi:[1,1,0]
	v_max_i32_e32 v13, 0, v13
	v_mul_f32_e32 v6, v103, v35
	v_mul_f32_e32 v12, v105, v9
	v_pk_fma_f32 v[2:3], v[102:103], v[34:35], v[2:3]
	v_pk_fma_f32 v[4:5], v[104:105], v[8:9], v[4:5]
	v_pk_add_f32 v[2:3], v[2:3], v[6:7] op_sel_hi:[1,0]
	v_pk_add_f32 v[4:5], v[4:5], v[12:13] op_sel_hi:[1,0]
	v_mul_f32_e32 v0, v108, v0
	s_nop 0
	v_permlane32_swap_b32_e32 v2, v4
	v_add_f32_e32 v2, v2, v4
	v_mul_f32_e32 v1, v109, v1
	v_add_f32_e32 v2, 0, v2
	v_fmac_f32_e32 v0, v106, v36
	v_fmac_f32_e32 v1, v107, v14
	v_ashrrev_i32_e32 v3, 31, v2
	v_fmac_f32_e32 v0, v110, v37
	v_fmac_f32_e32 v1, v111, v7
	v_bitop3_b32 v2, v3, v2, s33 bitop3:0x36
	v_fmac_f32_e32 v0, v112, v13
	v_fmac_f32_e32 v1, v113, v11
	v_cndmask_b32_e32 v2, 0, v2, vcc
	s_nop 0
	v_permlane32_swap_b32_e32 v0, v1
	v_cmp_ne_u32_e32 vcc, 0, v2
	ds_write_b32 v119, v2
	s_and_saveexec_b64 s[44:45], vcc
	s_cbranch_execz .LBB0_419
	v_lshrrev_b32_e32 v3, 20, v2
	v_lshrrev_b32_e32 v2, 17, v2
	v_and_b32_e32 v3, 0xffc, v3
	v_and_b32_e32 v2, 16, v2
	v_add_u32_e32 v3, v115, v3
	v_lshlrev_b32_e64 v2, v2, 1
	ds_add_u32 v3, v2

.LBB0_421:
	s_or_b64 exec, exec, s[44:45]
	s_add_i32 s48, s46, -5
	s_cmp_ge_u32 s48, s81
	s_cbranch_scc1 .LBB0_439
	s_waitcnt vmcnt(8)
	s_setprio 1
	v_mfma_f32_32x32x16_bf16 v[0:15], v[28:31], v[76:79], 0
	v_mfma_f32_32x32x16_bf16 v[0:15], v[20:23], v[72:75], v[0:15]
	v_mfma_f32_32x32x16_bf16 v[0:15], v[16:19], v[68:71], v[0:15]
	v_mfma_f32_32x32x16_bf16 v[0:15], v[24:27], v[64:67], v[0:15]
	v_add_u32_e32 v64, 0x100, v118
	v_cmp_le_i32_e32 vcc, v64, v114
	s_setprio 0
	s_add_i32 s48, s46, -5
	s_add_i32 s47, s46, -2
	s_cmp_lt_u32 s47, s81
	s_cselect_b32 s36, s47, s39
	s_lshl_b32 s36, s36, 5
	s_add_i32 s36, s36, s76
	s_ashr_i32 s37, s36, 31
	s_lshl_b64 s[44:45], s[36:37], 10
	v_lshl_add_u64 v[244:245], v[96:97], 0, s[44:45]
	s_or_b32 s44, s36, 1
	s_ashr_i32 s45, s44, 31
	s_lshl_b64 s[44:45], s[44:45], 10
	v_lshl_add_u64 v[246:247], v[96:97], 0, s[44:45]
	s_or_b32 s44, s36, 2
	s_ashr_i32 s45, s44, 31
	s_or_b32 s36, s36, 3
	s_lshl_b64 s[44:45], s[44:45], 10
	s_ashr_i32 s37, s36, 31
	global_load_dwordx4 v[36:39], v[244:245], off
	global_load_dwordx4 v[32:35], v[246:247], off
	v_lshl_add_u64 v[244:245], v[96:97], 0, s[44:45]
	s_lshl_b64 s[36:37], s[36:37], 10
	v_lshl_add_u64 v[246:247], v[96:97], 0, s[36:37]
	global_load_dwordx4 v[44:47], v[244:245], off
	global_load_dwordx4 v[40:43], v[246:247], off
	s_nop 3
	v_max_i32_e32 v67, 0, v4
	v_max_i32_e32 v66, 0, v0
	v_mul_f32_e32 v0, v99, v67
	v_pk_fma_f32 v[66:67], v[98:99], v[66:67], v[0:1] op_sel_hi:[1,1,0]
	v_max_i32_e32 v69, 0, v12
	v_max_i32_e32 v68, 0, v8
	v_pk_fma_f32 v[66:67], v[102:103], v[68:69], v[66:67]
	v_mul_f32_e32 v0, v103, v69
	v_pk_add_f32 v[66:67], v[66:67], v[0:1] op_sel_hi:[1,0]
	v_max_i32_e32 v0, 0, v5
	v_max_i32_e32 v1, 0, v1
	v_mul_f32_e32 v0, v108, v0
	v_max_i32_e32 v5, 0, v6
	v_fmac_f32_e32 v0, v106, v1
	v_max_i32_e32 v1, 0, v9
	v_max_i32_e32 v4, 0, v2
	v_mul_f32_e32 v2, v101, v5
	v_fmac_f32_e32 v0, v110, v1
	v_max_i32_e32 v1, 0, v13
	v_pk_fma_f32 v[4:5], v[100:101], v[4:5], v[2:3] op_sel_hi:[1,1,0]
	v_max_i32_e32 v9, 0, v14
	v_max_i32_e32 v8, 0, v10
	v_fmac_f32_e32 v0, v112, v1
	v_pk_fma_f32 v[4:5], v[104:105], v[8:9], v[4:5]
	v_mul_f32_e32 v2, v105, v9
	v_max_i32_e32 v1, 0, v7
	v_pk_add_f32 v[4:5], v[4:5], v[2:3] op_sel_hi:[1,0]
	v_max_i32_e32 v2, 0, v3
	v_mul_f32_e32 v1, v109, v1
	v_fmac_f32_e32 v1, v107, v2
	v_max_i32_e32 v2, 0, v11
	v_fmac_f32_e32 v1, v111, v2
	v_max_i32_e32 v2, 0, v15
	v_permlane32_swap_b32_e32 v66, v4
	v_fmac_f32_e32 v1, v113, v2
	v_add_f32_e32 v2, v66, v4
	v_add_f32_e32 v2, 0, v2
	v_ashrrev_i32_e32 v3, 31, v2
	v_bitop3_b32 v2, v3, v2, s33 bitop3:0x36
	v_cndmask_b32_e32 v2, 0, v2, vcc
	v_permlane32_swap_b32_e32 v0, v1
	v_cmp_ne_u32_e32 vcc, 0, v2
	ds_write_b32 v119, v2 offset:1024
	s_and_saveexec_b64 s[44:45], vcc
	s_cbranch_execz .LBB0_425
	v_lshrrev_b32_e32 v3, 20, v2
	v_lshrrev_b32_e32 v2, 17, v2
	v_and_b32_e32 v3, 0xffc, v3
	v_and_b32_e32 v2, 16, v2
	v_add_u32_e32 v3, v115, v3
	v_lshlrev_b32_e64 v2, v2, 1
	ds_add_u32 v3, v2

.LBB0_427:
	s_or_b64 exec, exec, s[44:45]
	s_add_i32 s48, s46, -4
	s_cmp_ge_u32 s48, s81
	s_cbranch_scc1 .LBB0_439
	s_waitcnt vmcnt(8)
	s_setprio 1
	v_mfma_f32_32x32x16_bf16 v[0:15], v[28:31], v[60:63], 0
	v_mfma_f32_32x32x16_bf16 v[0:15], v[20:23], v[56:59], v[0:15]
	v_mfma_f32_32x32x16_bf16 v[0:15], v[16:19], v[52:55], v[0:15]
	v_mfma_f32_32x32x16_bf16 v[0:15], v[24:27], v[48:51], v[0:15]
	v_add_u32_e32 v48, 0x200, v118
	v_cmp_le_i32_e32 vcc, v48, v114
	s_setprio 0
	s_add_i32 s48, s46, -4
	s_add_i32 s36, s46, -1
	s_cmp_lt_u32 s36, s81
	s_cselect_b32 s36, s36, s39
	s_lshl_b32 s36, s36, 5
	s_add_i32 s36, s36, s76
	s_ashr_i32 s37, s36, 31
	s_lshl_b64 s[44:45], s[36:37], 10
	v_lshl_add_u64 v[244:245], v[96:97], 0, s[44:45]
	s_or_b32 s44, s36, 1
	s_ashr_i32 s45, s44, 31
	s_lshl_b64 s[44:45], s[44:45], 10
	v_lshl_add_u64 v[246:247], v[96:97], 0, s[44:45]
	s_or_b32 s44, s36, 2
	s_ashr_i32 s45, s44, 31
	s_or_b32 s36, s36, 3
	s_lshl_b64 s[44:45], s[44:45], 10
	s_ashr_i32 s37, s36, 31
	global_load_dwordx4 v[76:79], v[244:245], off
	global_load_dwordx4 v[72:75], v[246:247], off
	v_lshl_add_u64 v[244:245], v[96:97], 0, s[44:45]
	s_lshl_b64 s[36:37], s[36:37], 10
	v_lshl_add_u64 v[246:247], v[96:97], 0, s[36:37]
	global_load_dwordx4 v[68:71], v[244:245], off
	global_load_dwordx4 v[64:67], v[246:247], off
	s_nop 3
	v_max_i32_e32 v51, 0, v4
	v_max_i32_e32 v50, 0, v0
	v_mul_f32_e32 v0, v99, v51
	v_pk_fma_f32 v[50:51], v[98:99], v[50:51], v[0:1] op_sel_hi:[1,1,0]
	v_max_i32_e32 v53, 0, v12
	v_max_i32_e32 v52, 0, v8
	v_pk_fma_f32 v[50:51], v[102:103], v[52:53], v[50:51]
	v_mul_f32_e32 v0, v103, v53
	v_pk_add_f32 v[50:51], v[50:51], v[0:1] op_sel_hi:[1,0]
	v_max_i32_e32 v0, 0, v5
	v_max_i32_e32 v1, 0, v1
	v_mul_f32_e32 v0, v108, v0
	v_max_i32_e32 v5, 0, v6
	v_fmac_f32_e32 v0, v106, v1
	v_max_i32_e32 v1, 0, v9
	v_max_i32_e32 v4, 0, v2
	v_mul_f32_e32 v2, v101, v5
	v_fmac_f32_e32 v0, v110, v1
	v_max_i32_e32 v1, 0, v13
	v_pk_fma_f32 v[4:5], v[100:101], v[4:5], v[2:3] op_sel_hi:[1,1,0]
	v_max_i32_e32 v9, 0, v14
	v_max_i32_e32 v8, 0, v10
	v_fmac_f32_e32 v0, v112, v1
	v_pk_fma_f32 v[4:5], v[104:105], v[8:9], v[4:5]
	v_mul_f32_e32 v2, v105, v9
	v_max_i32_e32 v1, 0, v7
	v_pk_add_f32 v[4:5], v[4:5], v[2:3] op_sel_hi:[1,0]
	v_max_i32_e32 v2, 0, v3
	v_mul_f32_e32 v1, v109, v1
	v_fmac_f32_e32 v1, v107, v2
	v_max_i32_e32 v2, 0, v11
	v_fmac_f32_e32 v1, v111, v2
	v_max_i32_e32 v2, 0, v15
	v_permlane32_swap_b32_e32 v50, v4
	v_fmac_f32_e32 v1, v113, v2
	v_add_f32_e32 v2, v50, v4
	v_add_f32_e32 v2, 0, v2
	v_ashrrev_i32_e32 v3, 31, v2
	v_bitop3_b32 v2, v3, v2, s33 bitop3:0x36
	v_cndmask_b32_e32 v2, 0, v2, vcc
	v_permlane32_swap_b32_e32 v0, v1
	v_cmp_ne_u32_e32 vcc, 0, v2
	ds_write_b32 v119, v2 offset:2048
	s_and_saveexec_b64 s[44:45], vcc
	s_cbranch_execz .LBB0_431
	v_lshrrev_b32_e32 v3, 20, v2
	v_lshrrev_b32_e32 v2, 17, v2
	v_and_b32_e32 v3, 0xffc, v3
	v_and_b32_e32 v2, 16, v2
	v_add_u32_e32 v3, v115, v3
	v_lshlrev_b32_e64 v2, v2, 1
	ds_add_u32 v3, v2

.LBB0_433:
	s_or_b64 exec, exec, s[44:45]
	s_add_i32 s48, s46, -3
	s_cmp_ge_u32 s48, s81
	s_cbranch_scc1 .LBB0_439
	s_waitcnt vmcnt(8)
	s_setprio 1
	v_mfma_f32_32x32x16_bf16 v[0:15], v[28:31], v[84:87], 0
	v_mfma_f32_32x32x16_bf16 v[0:15], v[20:23], v[80:83], v[0:15]
	v_add_u32_e32 v80, 0x300, v118
	v_cmp_le_i32_e32 vcc, v80, v114
	v_mfma_f32_32x32x16_bf16 v[0:15], v[16:19], v[88:91], v[0:15]
	v_mfma_f32_32x32x16_bf16 v[0:15], v[24:27], v[92:95], v[0:15]
	s_setprio 0
	s_cmp_lt_u32 s46, s81
	s_cselect_b32 s36, s46, s39
	s_lshl_b32 s36, s36, 5
	s_add_i32 s36, s36, s76
	s_ashr_i32 s37, s36, 31
	s_lshl_b64 s[44:45], s[36:37], 10
	v_lshl_add_u64 v[244:245], v[96:97], 0, s[44:45]
	s_or_b32 s44, s36, 1
	s_ashr_i32 s45, s44, 31
	s_lshl_b64 s[44:45], s[44:45], 10
	v_lshl_add_u64 v[246:247], v[96:97], 0, s[44:45]
	s_or_b32 s44, s36, 2
	s_ashr_i32 s45, s44, 31
	s_or_b32 s36, s36, 3
	s_lshl_b64 s[44:45], s[44:45], 10
	s_ashr_i32 s37, s36, 31
	global_load_dwordx4 v[60:63], v[244:245], off
	global_load_dwordx4 v[56:59], v[246:247], off
	v_lshl_add_u64 v[244:245], v[96:97], 0, s[44:45]
	s_lshl_b64 s[36:37], s[36:37], 10
	v_lshl_add_u64 v[246:247], v[96:97], 0, s[36:37]
	global_load_dwordx4 v[52:55], v[244:245], off
	global_load_dwordx4 v[48:51], v[246:247], off
	s_nop 3
	v_max_i32_e32 v83, 0, v4
	v_max_i32_e32 v82, 0, v0
	v_mul_f32_e32 v0, v99, v83
	v_pk_fma_f32 v[82:83], v[98:99], v[82:83], v[0:1] op_sel_hi:[1,1,0]
	v_max_i32_e32 v85, 0, v12
	v_max_i32_e32 v84, 0, v8
	v_pk_fma_f32 v[82:83], v[102:103], v[84:85], v[82:83]
	v_mul_f32_e32 v0, v103, v85
	v_pk_add_f32 v[82:83], v[82:83], v[0:1] op_sel_hi:[1,0]
	v_max_i32_e32 v0, 0, v5
	v_max_i32_e32 v1, 0, v1
	v_mul_f32_e32 v0, v108, v0
	v_max_i32_e32 v5, 0, v6
	v_fmac_f32_e32 v0, v106, v1
	v_max_i32_e32 v1, 0, v9
	v_max_i32_e32 v4, 0, v2
	v_mul_f32_e32 v2, v101, v5
	v_fmac_f32_e32 v0, v110, v1
	v_max_i32_e32 v1, 0, v13
	v_pk_fma_f32 v[4:5], v[100:101], v[4:5], v[2:3] op_sel_hi:[1,1,0]
	v_max_i32_e32 v9, 0, v14
	v_max_i32_e32 v8, 0, v10
	v_fmac_f32_e32 v0, v112, v1
	v_pk_fma_f32 v[4:5], v[104:105], v[8:9], v[4:5]
	v_mul_f32_e32 v2, v105, v9
	v_max_i32_e32 v1, 0, v7
	v_pk_add_f32 v[4:5], v[4:5], v[2:3] op_sel_hi:[1,0]
	v_max_i32_e32 v2, 0, v3
	v_mul_f32_e32 v1, v109, v1
	v_fmac_f32_e32 v1, v107, v2
	v_max_i32_e32 v2, 0, v11
	v_fmac_f32_e32 v1, v111, v2
	v_max_i32_e32 v2, 0, v15
	v_permlane32_swap_b32_e32 v82, v4
	v_fmac_f32_e32 v1, v113, v2
	v_add_f32_e32 v2, v82, v4
	v_add_f32_e32 v2, 0, v2
	v_ashrrev_i32_e32 v3, 31, v2
	v_bitop3_b32 v2, v3, v2, s33 bitop3:0x36
	v_cndmask_b32_e32 v2, 0, v2, vcc
	v_permlane32_swap_b32_e32 v0, v1
	v_cmp_ne_u32_e32 vcc, 0, v2
	ds_write_b32 v119, v2 offset:3072
	s_and_saveexec_b64 s[42:43], vcc
	s_cbranch_execz .LBB0_437
	v_lshrrev_b32_e32 v3, 20, v2
	v_lshrrev_b32_e32 v2, 17, v2
	v_and_b32_e32 v3, 0xffc, v3
	v_and_b32_e32 v2, 16, v2
	v_add_u32_e32 v3, v115, v3
	v_lshlrev_b32_e64 v2, v2, 1
	ds_add_u32 v3, v2
